# norm1 phase bias matvec: xor-1/2/4/8 butterfly steps by DPP instead of ds_bpermute round trips (same add order)
# baseline (speedup 1.0000x reference)
.LBB0_132:
	s_waitcnt lgkmcnt(0)
	v_lshl_add_u64 v[34:35], s[82:83], 0, v[16:17]
	global_load_dwordx2 v[36:37], v[34:35], off offset:-1024
	global_load_dwordx2 v[38:39], v[34:35], off offset:-512
	global_load_dwordx2 v[46:47], v[34:35], off
	global_load_dwordx2 v[48:49], v[34:35], off offset:512
	global_load_dwordx4 v[50:53], v[0:1], off
	global_load_dwordx4 v[54:57], v[0:1], off offset:1024
	global_load_dwordx4 v[58:61], v[0:1], off offset:2048
	global_load_dwordx4 v[62:65], v[0:1], off offset:3072
	s_add_u32 s14, s82, s6
	s_addc_u32 s15, s83, s7
	s_waitcnt vmcnt(7)
	v_and_b32_e32 v41, 0xffff0000, v36
	v_and_b32_e32 v42, 0xffff0000, v37
	v_lshlrev_b32_e32 v33, 16, v36
	v_lshlrev_b32_e32 v34, 16, v37
	s_waitcnt vmcnt(6)
	v_lshlrev_b32_e32 v35, 16, v38
	v_and_b32_e32 v43, 0xffff0000, v38
	v_and_b32_e32 v44, 0xffff0000, v39
	s_waitcnt vmcnt(5)
	v_lshlrev_b32_e32 v37, 16, v46
	v_and_b32_e32 v45, 0xffff0000, v46
	v_lshlrev_b32_e32 v38, 16, v47
	v_and_b32_e32 v46, 0xffff0000, v47
	s_waitcnt vmcnt(4)
	v_lshlrev_b32_e32 v40, 16, v49
	v_and_b32_e32 v47, 0xffff0000, v49
	s_waitcnt vmcnt(3)
	v_mul_f32_e32 v49, v51, v41
	v_mul_f32_e32 v51, v53, v42
	v_lshlrev_b32_e32 v36, 16, v39
	s_waitcnt vmcnt(2)
	v_mul_f32_e32 v53, v55, v43
	v_mul_f32_e32 v55, v57, v44
	v_fmac_f32_e32 v49, v50, v33
	v_fmac_f32_e32 v51, v52, v34
	v_lshlrev_b32_e32 v39, 16, v48
	v_and_b32_e32 v48, 0xffff0000, v48
	s_waitcnt vmcnt(1)
	v_mul_f32_e32 v57, v59, v45
	v_mul_f32_e32 v59, v61, v46
	v_fmac_f32_e32 v53, v54, v35
	v_fmac_f32_e32 v55, v56, v36
	v_add_f32_e32 v49, v49, v51
	s_waitcnt vmcnt(0)
	v_mul_f32_e32 v61, v63, v48
	v_mul_f32_e32 v63, v65, v47
	v_fmac_f32_e32 v57, v58, v37
	v_fmac_f32_e32 v59, v60, v38
	v_add_f32_e32 v50, v53, v55
	v_add_f32_e32 v49, 0, v49
	v_fmac_f32_e32 v61, v62, v39
	v_fmac_f32_e32 v63, v64, v40
	v_add_f32_e32 v51, v57, v59
	v_add_f32_e32 v49, v49, v50
	v_add_f32_e32 v49, v49, v51
	v_add_f32_e32 v50, v61, v63
	v_add_f32_e32 v49, v49, v50
	s_nop 1
	v_add_f32_dpp v49, v49, v49 quad_perm:[1,0,3,2] row_mask:0xf bank_mask:0xf
	s_nop 1
	v_add_f32_dpp v49, v49, v49 quad_perm:[2,3,0,1] row_mask:0xf bank_mask:0xf
	s_nop 1
	v_add_f32_dpp v49, v49, v49 row_half_mirror row_mask:0xf bank_mask:0xf
	s_nop 1
	v_add_f32_dpp v49, v49, v49 row_mirror row_mask:0xf bank_mask:0xf
	ds_bpermute_b32 v50, v23, v49
	s_waitcnt lgkmcnt(0)
	v_add_f32_e32 v49, v49, v50
	ds_bpermute_b32 v50, v24, v49
	s_and_saveexec_b64 s[16:17], vcc
	s_cbranch_execz .LBB0_134
	s_waitcnt lgkmcnt(0)
	v_add_f32_e32 v49, v49, v50
	global_store_dword v25, v49, s[14:15]
.LBB0_134:
	s_or_b64 exec, exec, s[16:17]
	s_waitcnt lgkmcnt(0)
	global_load_dwordx4 v[50:53], v[2:3], off
	global_load_dwordx4 v[54:57], v[2:3], off offset:1024
	global_load_dwordx4 v[58:61], v[2:3], off offset:2048
	global_load_dwordx4 v[62:65], v[2:3], off offset:3072
	s_waitcnt vmcnt(3)
	v_mul_f32_e32 v49, v51, v41
	v_mul_f32_e32 v51, v53, v42
	s_waitcnt vmcnt(2)
	v_mul_f32_e32 v53, v55, v43
	v_mul_f32_e32 v55, v57, v44
	v_fmac_f32_e32 v49, v50, v33
	v_fmac_f32_e32 v51, v52, v34
	s_waitcnt vmcnt(1)
	v_mul_f32_e32 v57, v59, v45
	v_mul_f32_e32 v59, v61, v46
	v_fmac_f32_e32 v53, v54, v35
	v_fmac_f32_e32 v55, v56, v36
	v_add_f32_e32 v49, v49, v51
	s_waitcnt vmcnt(0)
	v_mul_f32_e32 v61, v63, v48
	v_mul_f32_e32 v63, v65, v47
	v_fmac_f32_e32 v57, v58, v37
	v_fmac_f32_e32 v59, v60, v38
	v_add_f32_e32 v50, v53, v55
	v_add_f32_e32 v49, 0, v49
	v_fmac_f32_e32 v61, v62, v39
	v_fmac_f32_e32 v63, v64, v40
	v_add_f32_e32 v51, v57, v59
	v_add_f32_e32 v49, v49, v50
	v_add_f32_e32 v49, v49, v51
	v_add_f32_e32 v50, v61, v63
	v_add_f32_e32 v49, v49, v50
	s_nop 1
	v_add_f32_dpp v49, v49, v49 quad_perm:[1,0,3,2] row_mask:0xf bank_mask:0xf
	s_nop 1
	v_add_f32_dpp v49, v49, v49 quad_perm:[2,3,0,1] row_mask:0xf bank_mask:0xf
	s_nop 1
	v_add_f32_dpp v49, v49, v49 row_half_mirror row_mask:0xf bank_mask:0xf
	s_nop 1
	v_add_f32_dpp v49, v49, v49 row_mirror row_mask:0xf bank_mask:0xf
	ds_bpermute_b32 v50, v23, v49
	s_waitcnt lgkmcnt(0)
	v_add_f32_e32 v49, v49, v50
	ds_bpermute_b32 v50, v24, v49
	s_and_saveexec_b64 s[16:17], vcc
	s_cbranch_execz .LBB0_136
	s_waitcnt lgkmcnt(0)
	v_add_f32_e32 v49, v49, v50
	global_store_dword v26, v49, s[14:15] offset:2048
.LBB0_136:
	s_or_b64 exec, exec, s[16:17]
	s_waitcnt lgkmcnt(0)
	global_load_dwordx4 v[50:53], v[4:5], off
	global_load_dwordx4 v[54:57], v[4:5], off offset:1024
	global_load_dwordx4 v[58:61], v[4:5], off offset:2048
	global_load_dwordx4 v[62:65], v[4:5], off offset:3072
	s_waitcnt vmcnt(3)
	v_mul_f32_e32 v49, v51, v41
	v_mul_f32_e32 v51, v53, v42
	s_waitcnt vmcnt(2)
	v_mul_f32_e32 v53, v55, v43
	v_mul_f32_e32 v55, v57, v44
	v_fmac_f32_e32 v49, v50, v33
	v_fmac_f32_e32 v51, v52, v34
	s_waitcnt vmcnt(1)
	v_mul_f32_e32 v57, v59, v45
	v_mul_f32_e32 v59, v61, v46
	v_fmac_f32_e32 v53, v54, v35
	v_fmac_f32_e32 v55, v56, v36
	v_add_f32_e32 v49, v49, v51
	s_waitcnt vmcnt(0)
	v_mul_f32_e32 v61, v63, v48
	v_mul_f32_e32 v63, v65, v47
	v_fmac_f32_e32 v57, v58, v37
	v_fmac_f32_e32 v59, v60, v38
	v_add_f32_e32 v50, v53, v55
	v_add_f32_e32 v49, 0, v49
	v_fmac_f32_e32 v61, v62, v39
	v_fmac_f32_e32 v63, v64, v40
	v_add_f32_e32 v51, v57, v59
	v_add_f32_e32 v49, v49, v50
	v_add_f32_e32 v49, v49, v51
	v_add_f32_e32 v50, v61, v63
	v_add_f32_e32 v49, v49, v50
	s_nop 1
	v_add_f32_dpp v49, v49, v49 quad_perm:[1,0,3,2] row_mask:0xf bank_mask:0xf
	s_nop 1
	v_add_f32_dpp v49, v49, v49 quad_perm:[2,3,0,1] row_mask:0xf bank_mask:0xf
	s_nop 1
	v_add_f32_dpp v49, v49, v49 row_half_mirror row_mask:0xf bank_mask:0xf
	s_nop 1
	v_add_f32_dpp v49, v49, v49 row_mirror row_mask:0xf bank_mask:0xf
	ds_bpermute_b32 v50, v23, v49
	s_waitcnt lgkmcnt(0)
	v_add_f32_e32 v49, v49, v50
	ds_bpermute_b32 v50, v24, v49
	s_and_saveexec_b64 s[16:17], vcc
	s_cbranch_execz .LBB0_138
	s_waitcnt lgkmcnt(0)
	v_add_f32_e32 v49, v49, v50
	global_store_dword v27, v49, s[14:15]
.LBB0_138:
	s_or_b64 exec, exec, s[16:17]
	s_waitcnt lgkmcnt(0)
	global_load_dwordx4 v[50:53], v[6:7], off
	global_load_dwordx4 v[54:57], v[6:7], off offset:1024
	global_load_dwordx4 v[58:61], v[6:7], off offset:2048
	global_load_dwordx4 v[62:65], v[6:7], off offset:3072
	s_waitcnt vmcnt(3)
	v_mul_f32_e32 v49, v51, v41
	v_mul_f32_e32 v51, v53, v42
	s_waitcnt vmcnt(2)
	v_mul_f32_e32 v53, v55, v43
	v_mul_f32_e32 v55, v57, v44
	v_fmac_f32_e32 v49, v50, v33
	v_fmac_f32_e32 v51, v52, v34
	s_waitcnt vmcnt(1)
	v_mul_f32_e32 v57, v59, v45
	v_mul_f32_e32 v59, v61, v46
	v_fmac_f32_e32 v53, v54, v35
	v_fmac_f32_e32 v55, v56, v36
	v_add_f32_e32 v49, v49, v51
	s_waitcnt vmcnt(0)
	v_mul_f32_e32 v61, v63, v48
	v_mul_f32_e32 v63, v65, v47
	v_fmac_f32_e32 v57, v58, v37
	v_fmac_f32_e32 v59, v60, v38
	v_add_f32_e32 v50, v53, v55
	v_add_f32_e32 v49, 0, v49
	v_fmac_f32_e32 v61, v62, v39
	v_fmac_f32_e32 v63, v64, v40
	v_add_f32_e32 v51, v57, v59
	v_add_f32_e32 v49, v49, v50
	v_add_f32_e32 v49, v49, v51
	v_add_f32_e32 v50, v61, v63
	v_add_f32_e32 v49, v49, v50
	s_nop 1
	v_add_f32_dpp v49, v49, v49 quad_perm:[1,0,3,2] row_mask:0xf bank_mask:0xf
	s_nop 1
	v_add_f32_dpp v49, v49, v49 quad_perm:[2,3,0,1] row_mask:0xf bank_mask:0xf
	s_nop 1
	v_add_f32_dpp v49, v49, v49 row_half_mirror row_mask:0xf bank_mask:0xf
	s_nop 1
	v_add_f32_dpp v49, v49, v49 row_mirror row_mask:0xf bank_mask:0xf
	ds_bpermute_b32 v50, v23, v49
	s_waitcnt lgkmcnt(0)
	v_add_f32_e32 v49, v49, v50
	ds_bpermute_b32 v50, v24, v49
	s_and_saveexec_b64 s[16:17], vcc
	s_cbranch_execz .LBB0_140
	s_waitcnt lgkmcnt(0)
	v_add_f32_e32 v49, v49, v50
	global_store_dword v28, v49, s[14:15] offset:2048
.LBB0_140:
	s_or_b64 exec, exec, s[16:17]
	s_waitcnt lgkmcnt(0)
	global_load_dwordx4 v[50:53], v[8:9], off
	global_load_dwordx4 v[54:57], v[8:9], off offset:1024
	global_load_dwordx4 v[58:61], v[8:9], off offset:2048
	global_load_dwordx4 v[62:65], v[8:9], off offset:3072
	s_waitcnt vmcnt(3)
	v_mul_f32_e32 v49, v51, v41
	v_mul_f32_e32 v51, v53, v42
	s_waitcnt vmcnt(2)
	v_mul_f32_e32 v53, v55, v43
	v_mul_f32_e32 v55, v57, v44
	v_fmac_f32_e32 v49, v50, v33
	v_fmac_f32_e32 v51, v52, v34
	s_waitcnt vmcnt(1)
	v_mul_f32_e32 v57, v59, v45
	v_mul_f32_e32 v59, v61, v46
	v_fmac_f32_e32 v53, v54, v35
	v_fmac_f32_e32 v55, v56, v36
	v_add_f32_e32 v49, v49, v51
	s_waitcnt vmcnt(0)
	v_mul_f32_e32 v61, v63, v48
	v_mul_f32_e32 v63, v65, v47
	v_fmac_f32_e32 v57, v58, v37
	v_fmac_f32_e32 v59, v60, v38
	v_add_f32_e32 v50, v53, v55
	v_add_f32_e32 v49, 0, v49
	v_fmac_f32_e32 v61, v62, v39
	v_fmac_f32_e32 v63, v64, v40
	v_add_f32_e32 v51, v57, v59
	v_add_f32_e32 v49, v49, v50
	v_add_f32_e32 v49, v49, v51
	v_add_f32_e32 v50, v61, v63
	v_add_f32_e32 v49, v49, v50
	s_nop 1
	v_add_f32_dpp v49, v49, v49 quad_perm:[1,0,3,2] row_mask:0xf bank_mask:0xf
	s_nop 1
	v_add_f32_dpp v49, v49, v49 quad_perm:[2,3,0,1] row_mask:0xf bank_mask:0xf
	s_nop 1
	v_add_f32_dpp v49, v49, v49 row_half_mirror row_mask:0xf bank_mask:0xf
	s_nop 1
	v_add_f32_dpp v49, v49, v49 row_mirror row_mask:0xf bank_mask:0xf
	ds_bpermute_b32 v50, v23, v49
	s_waitcnt lgkmcnt(0)
	v_add_f32_e32 v49, v49, v50
	ds_bpermute_b32 v50, v24, v49
	s_and_saveexec_b64 s[16:17], vcc
	s_cbranch_execz .LBB0_142
	s_waitcnt lgkmcnt(0)
	v_add_f32_e32 v49, v49, v50
	global_store_dword v29, v49, s[14:15]
.LBB0_142:
	s_or_b64 exec, exec, s[16:17]
	s_waitcnt lgkmcnt(0)
	global_load_dwordx4 v[50:53], v[10:11], off
	global_load_dwordx4 v[54:57], v[10:11], off offset:1024
	global_load_dwordx4 v[58:61], v[10:11], off offset:2048
	global_load_dwordx4 v[62:65], v[10:11], off offset:3072
	s_waitcnt vmcnt(3)
	v_mul_f32_e32 v49, v51, v41
	v_mul_f32_e32 v51, v53, v42
	s_waitcnt vmcnt(2)
	v_mul_f32_e32 v53, v55, v43
	v_mul_f32_e32 v55, v57, v44
	v_fmac_f32_e32 v49, v50, v33
	v_fmac_f32_e32 v51, v52, v34
	s_waitcnt vmcnt(1)
	v_mul_f32_e32 v57, v59, v45
	v_mul_f32_e32 v59, v61, v46
	v_fmac_f32_e32 v53, v54, v35
	v_fmac_f32_e32 v55, v56, v36
	v_add_f32_e32 v49, v49, v51
	s_waitcnt vmcnt(0)
	v_mul_f32_e32 v61, v63, v48
	v_mul_f32_e32 v63, v65, v47
	v_fmac_f32_e32 v57, v58, v37
	v_fmac_f32_e32 v59, v60, v38
	v_add_f32_e32 v50, v53, v55
	v_add_f32_e32 v49, 0, v49
	v_fmac_f32_e32 v61, v62, v39
	v_fmac_f32_e32 v63, v64, v40
	v_add_f32_e32 v51, v57, v59
	v_add_f32_e32 v49, v49, v50
	v_add_f32_e32 v49, v49, v51
	v_add_f32_e32 v50, v61, v63
	v_add_f32_e32 v49, v49, v50
	s_nop 1
	v_add_f32_dpp v49, v49, v49 quad_perm:[1,0,3,2] row_mask:0xf bank_mask:0xf
	s_nop 1
	v_add_f32_dpp v49, v49, v49 quad_perm:[2,3,0,1] row_mask:0xf bank_mask:0xf
	s_nop 1
	v_add_f32_dpp v49, v49, v49 row_half_mirror row_mask:0xf bank_mask:0xf
	s_nop 1
	v_add_f32_dpp v49, v49, v49 row_mirror row_mask:0xf bank_mask:0xf
	ds_bpermute_b32 v50, v23, v49
	s_waitcnt lgkmcnt(0)
	v_add_f32_e32 v49, v49, v50
	ds_bpermute_b32 v50, v24, v49
	s_and_saveexec_b64 s[16:17], vcc
	s_cbranch_execz .LBB0_144
	s_waitcnt lgkmcnt(0)
	v_add_f32_e32 v49, v49, v50
	global_store_dword v30, v49, s[14:15] offset:2048
.LBB0_144:
	s_or_b64 exec, exec, s[16:17]
	s_waitcnt lgkmcnt(0)
	global_load_dwordx4 v[50:53], v[12:13], off
	global_load_dwordx4 v[54:57], v[12:13], off offset:1024
	global_load_dwordx4 v[58:61], v[12:13], off offset:2048
	global_load_dwordx4 v[62:65], v[12:13], off offset:3072
	s_waitcnt vmcnt(3)
	v_mul_f32_e32 v49, v51, v41
	v_mul_f32_e32 v51, v53, v42
	s_waitcnt vmcnt(2)
	v_mul_f32_e32 v53, v55, v43
	v_mul_f32_e32 v55, v57, v44
	v_fmac_f32_e32 v49, v50, v33
	v_fmac_f32_e32 v51, v52, v34
	s_waitcnt vmcnt(1)
	v_mul_f32_e32 v57, v59, v45
	v_mul_f32_e32 v59, v61, v46
	v_fmac_f32_e32 v53, v54, v35
	v_fmac_f32_e32 v55, v56, v36
	v_add_f32_e32 v49, v49, v51
	s_waitcnt vmcnt(0)
	v_mul_f32_e32 v61, v63, v48
	v_mul_f32_e32 v63, v65, v47
	v_fmac_f32_e32 v57, v58, v37
	v_fmac_f32_e32 v59, v60, v38
	v_add_f32_e32 v50, v53, v55
	v_add_f32_e32 v49, 0, v49
	v_fmac_f32_e32 v61, v62, v39
	v_fmac_f32_e32 v63, v64, v40
	v_add_f32_e32 v51, v57, v59
	v_add_f32_e32 v49, v49, v50
	v_add_f32_e32 v49, v49, v51
	v_add_f32_e32 v50, v61, v63
	v_add_f32_e32 v49, v49, v50
	s_nop 1
	v_add_f32_dpp v49, v49, v49 quad_perm:[1,0,3,2] row_mask:0xf bank_mask:0xf
	s_nop 1
	v_add_f32_dpp v49, v49, v49 quad_perm:[2,3,0,1] row_mask:0xf bank_mask:0xf
	s_nop 1
	v_add_f32_dpp v49, v49, v49 row_half_mirror row_mask:0xf bank_mask:0xf
	s_nop 1
	v_add_f32_dpp v49, v49, v49 row_mirror row_mask:0xf bank_mask:0xf
	ds_bpermute_b32 v50, v23, v49
	s_waitcnt lgkmcnt(0)
	v_add_f32_e32 v49, v49, v50
	ds_bpermute_b32 v50, v24, v49
	s_and_saveexec_b64 s[16:17], vcc
	s_cbranch_execz .LBB0_146
	s_waitcnt lgkmcnt(0)
	v_add_f32_e32 v49, v49, v50
	global_store_dword v31, v49, s[14:15]
.LBB0_146:
	s_or_b64 exec, exec, s[16:17]
	s_waitcnt lgkmcnt(0)
	global_load_dwordx4 v[50:53], v[14:15], off
	global_load_dwordx4 v[54:57], v[14:15], off offset:1024
	global_load_dwordx4 v[58:61], v[14:15], off offset:2048
	global_load_dwordx4 v[62:65], v[14:15], off offset:3072
	s_waitcnt vmcnt(3)
	v_mul_f32_e32 v41, v51, v41
	v_mul_f32_e32 v42, v53, v42
	s_waitcnt vmcnt(2)
	v_mul_f32_e32 v43, v55, v43
	v_mul_f32_e32 v44, v57, v44
	v_fmac_f32_e32 v41, v50, v33
	v_fmac_f32_e32 v42, v52, v34
	s_waitcnt vmcnt(1)
	v_mul_f32_e32 v45, v59, v45
	v_mul_f32_e32 v46, v61, v46
	v_fmac_f32_e32 v43, v54, v35
	v_fmac_f32_e32 v44, v56, v36
	v_add_f32_e32 v33, v41, v42
	s_waitcnt vmcnt(0)
	v_mul_f32_e32 v48, v63, v48
	v_mul_f32_e32 v47, v65, v47
	v_fmac_f32_e32 v45, v58, v37
	v_fmac_f32_e32 v46, v60, v38
	v_add_f32_e32 v34, v43, v44
	v_add_f32_e32 v33, 0, v33
	v_fmac_f32_e32 v48, v62, v39
	v_fmac_f32_e32 v47, v64, v40
	v_add_f32_e32 v35, v45, v46
	v_add_f32_e32 v33, v33, v34
	v_add_f32_e32 v33, v33, v35
	v_add_f32_e32 v34, v48, v47
	v_add_f32_e32 v33, v33, v34
	s_nop 1
	v_add_f32_dpp v33, v33, v33 quad_perm:[1,0,3,2] row_mask:0xf bank_mask:0xf
	s_nop 1
	v_add_f32_dpp v33, v33, v33 quad_perm:[2,3,0,1] row_mask:0xf bank_mask:0xf
	s_nop 1
	v_add_f32_dpp v33, v33, v33 row_half_mirror row_mask:0xf bank_mask:0xf
	s_nop 1
	v_add_f32_dpp v33, v33, v33 row_mirror row_mask:0xf bank_mask:0xf
	ds_bpermute_b32 v34, v23, v33
	s_waitcnt lgkmcnt(0)
	v_add_f32_e32 v33, v33, v34
	ds_bpermute_b32 v34, v24, v33
	s_and_saveexec_b64 s[16:17], vcc
	s_cbranch_execz .LBB0_131
	s_waitcnt lgkmcnt(0)
	v_add_f32_e32 v33, v33, v34
	global_store_dword v32, v33, s[14:15] offset:2048
	s_branch .LBB0_131
